# stack9 + attention unit prologue de-serialisation: second K/V tile loads issued with the first tile and Q loads
# baseline (speedup 1.0000x reference)
.LBB0_517:
	s_and_b64 s[28:29], s[36:37], exec
	s_cselect_b32 s10, 3, 1
	s_lshr_b32 s33, s0, s10
	s_and_b32 s10, s33, 15
	s_add_u32 s36, s18, s74
	s_addc_u32 s37, s19, s75
	s_add_u32 s38, s18, s72
	s_addc_u32 s39, s19, s73
	s_lshl_b32 s25, s33, 5
	s_and_b32 s25, s25, 0x180
	s_or_b32 s28, s6, s25
	s_lshl_b64 s[34:35], s[68:69], 11
	s_lshl_b32 s25, s10, 7
	s_or_b32 s34, s34, s25
	s_lshl_b64 s[70:71], s[34:35], 1
	s_mov_b32 s29, s7
	s_add_u32 s34, s60, s70
	s_addc_u32 s35, s61, s71
	s_lshl_b64 s[28:29], s[28:29], 1
	s_add_u32 s76, s38, s28
	s_addc_u32 s77, s39, s29
	s_add_u32 s78, s36, s28
	s_addc_u32 s79, s37, s29
	global_load_dwordx4 v[2:5], v203, s[78:79]
	global_load_dwordx4 v[6:9], v204, s[78:79]
	global_load_dwordx4 v[10:13], v203, s[76:77]
	global_load_dwordx4 v[14:17], v204, s[76:77]
	global_load_dwordx4 v[50:53], v206, s[78:79]
	global_load_dwordx4 v[54:57], v205, s[78:79]
	global_load_dwordx4 v[58:61], v205, s[76:77]
	global_load_dwordx4 v[62:65], v206, s[76:77]
	v_readfirstlane_b32 s29, v0
	s_lshr_b32 s28, s29, 6
	s_lshl_b32 s10, s28, 5
	v_or_b32_e32 v18, s10, v181
	v_mov_b32_e32 v19, v179
	v_lshlrev_b64 v[18:19], 12, v[18:19]
	v_lshl_add_u64 v[18:19], s[34:35], 0, v[18:19]
	v_lshl_add_u64 v[18:19], v[18:19], 0, v[184:185]
	global_load_dwordx4 v[126:129], v[18:19], off
	global_load_dwordx4 v[122:125], v[18:19], off offset:32
	global_load_dwordx4 v[118:121], v[18:19], off offset:64
	global_load_dwordx4 v[114:117], v[18:19], off offset:96
	global_load_dwordx4 v[110:113], v[18:19], off offset:128
	global_load_dwordx4 v[106:109], v[18:19], off offset:160
	global_load_dwordx4 v[102:105], v[18:19], off offset:192
	global_load_dwordx4 v[98:101], v[18:19], off offset:224
	s_waitcnt vmcnt(0)
	s_and_b32 s29, s29, 0x3fffffc0
	s_lshl_b32 s29, s29, 2
	s_add_i32 s29, s29, 0
	s_add_i32 s29, s29, 0x10000
	s_mov_b32 s36, s11
	s_mov_b32 s37, s11
	s_mov_b32 s38, s11
	s_mov_b32 s39, s11
	s_mov_b32 s40, s11
	s_mov_b32 s41, s11
	s_mov_b32 s42, s11
	s_mov_b32 s43, s11
	s_mov_b32 s44, s11
	s_mov_b32 s45, s11
	s_mov_b32 s46, s11
	s_mov_b32 s47, s11
	s_mov_b32 s48, s11
	s_mov_b32 s49, s11
	s_mov_b32 s50, s11
	s_mov_b32 s51, s11
	v_lshl_add_u32 v222, v181, 2, s29
	v_mov_b32_e32 v223, 0
	s_waitcnt vmcnt(0)
	ds_write_b128 v209, v[2:5]
	ds_write_b128 v210, v[6:9]
	ds_write_b128 v211, v[10:13] offset:32768
	ds_write_b128 v212, v[14:17] offset:32768
	s_waitcnt lgkmcnt(0)
	s_barrier
	ds_read_b128 v[2:5], v213 offset:32768
	ds_read_b128 v[6:9], v213 offset:40960
	s_waitcnt lgkmcnt(1)
	v_mfma_f32_32x32x16_bf16 v[18:33], v[2:5], v[126:129], 0
	s_waitcnt lgkmcnt(0)
	v_mfma_f32_32x32x16_bf16 v[34:49], v[6:9], v[126:129], 0
	ds_read_b128 v[2:5], v214 offset:32768
	ds_read_b128 v[6:9], v214 offset:40960
	s_waitcnt lgkmcnt(1)
	v_mfma_f32_32x32x16_bf16 v[18:33], v[2:5], v[122:125], v[18:33]
	s_waitcnt lgkmcnt(0)
	v_mfma_f32_32x32x16_bf16 v[34:49], v[6:9], v[122:125], v[34:49]
	ds_read_b128 v[2:5], v215 offset:32768
	ds_read_b128 v[6:9], v215 offset:40960
	s_waitcnt lgkmcnt(1)
	v_mfma_f32_32x32x16_bf16 v[18:33], v[2:5], v[118:121], v[18:33]
	s_waitcnt lgkmcnt(0)
	v_mfma_f32_32x32x16_bf16 v[34:49], v[6:9], v[118:121], v[34:49]
	ds_read_b128 v[2:5], v216 offset:32768
	ds_read_b128 v[6:9], v216 offset:40960
	s_waitcnt lgkmcnt(1)
	v_mfma_f32_32x32x16_bf16 v[18:33], v[2:5], v[114:117], v[18:33]
	s_waitcnt lgkmcnt(0)
	v_mfma_f32_32x32x16_bf16 v[34:49], v[6:9], v[114:117], v[34:49]
	ds_read_b128 v[2:5], v217 offset:32768
	ds_read_b128 v[6:9], v217 offset:40960
	s_waitcnt lgkmcnt(1)
	v_mfma_f32_32x32x16_bf16 v[18:33], v[2:5], v[110:113], v[18:33]
	s_waitcnt lgkmcnt(0)
	v_mfma_f32_32x32x16_bf16 v[34:49], v[6:9], v[110:113], v[34:49]
	ds_read_b128 v[2:5], v218 offset:32768
	ds_read_b128 v[6:9], v218 offset:40960
	ds_read_b128 v[66:69], v220 offset:32768
	ds_read_b128 v[70:73], v220 offset:40960
	s_waitcnt lgkmcnt(3)
	v_mfma_f32_32x32x16_bf16 v[18:33], v[2:5], v[106:109], v[18:33]
	ds_read_b128 v[2:5], v219 offset:32768
	s_waitcnt lgkmcnt(3)
	v_mfma_f32_32x32x16_bf16 v[34:49], v[6:9], v[106:109], v[34:49]
	ds_read_b128 v[6:9], v219 offset:40960
	global_load_dwordx4 v[142:145], v207, s[76:77]
	global_load_dwordx4 v[134:137], v207, s[78:79]
	global_load_dwordx4 v[138:141], v208, s[76:77]
	global_load_dwordx4 v[130:133], v208, s[78:79]
	s_waitcnt vmcnt(4)
	s_waitcnt vmcnt(6)
	ds_write_b128 v209, v[54:57] offset:16384
	ds_write_b128 v210, v[50:53] offset:16384
	s_waitcnt vmcnt(5)
	ds_write_b128 v211, v[58:61] offset:49152
	s_waitcnt vmcnt(4)
	ds_write_b128 v212, v[62:65] offset:49152
	s_waitcnt lgkmcnt(5)
	v_mfma_f32_32x32x16_bf16 v[18:33], v[2:5], v[102:105], v[18:33]
	s_waitcnt lgkmcnt(0)
	s_barrier
	v_mfma_f32_32x32x16_bf16 v[34:49], v[6:9], v[102:105], v[34:49]
	v_mov_b64_e32 v[2:3], s[36:37]
	v_mov_b64_e32 v[4:5], s[38:39]
	v_mov_b64_e32 v[6:7], s[40:41]
	v_mov_b64_e32 v[8:9], s[42:43]
	v_mov_b64_e32 v[10:11], s[44:45]
	v_mov_b64_e32 v[12:13], s[46:47]
	v_mov_b64_e32 v[14:15], s[48:49]
	v_mfma_f32_32x32x16_bf16 v[18:33], v[66:69], v[98:101], v[18:33]
	v_max3_f32 v66, v18, v19, v20
	v_mov_b64_e32 v[16:17], s[50:51]
	v_max3_f32 v66, v66, v21, v22
	s_nop 0
	v_max3_f32 v66, v66, v23, v24
	s_nop 9
	v_max_f32_e32 v69, v33, v33
	v_mfma_f32_32x32x16_bf16 v[34:49], v[70:73], v[98:101], v[34:49]
	v_max3_f32 v67, v34, v35, v36
	v_max3_f32 v66, v66, v25, v26
	s_nop 0
	v_max3_f32 v67, v67, v37, v38
	v_max3_f32 v66, v66, v27, v28
	s_nop 10
	v_max_f32_e32 v68, v49, v49
	v_max3_f32 v67, v67, v39, v40
	v_max3_f32 v66, v66, v29, v30
	v_max_f32_e32 v68, v69, v68
	v_max3_f32 v67, v67, v41, v42
	v_max3_f32 v66, v66, v31, v32
	s_nop 0
	v_max3_f32 v67, v67, v43, v44
	s_nop 0
	v_max3_f32 v67, v67, v45, v46
	s_nop 0
	v_max3_f32 v67, v67, v47, v48
	s_nop 0
	v_max3_f32 v66, v66, v67, v68
	s_nop 0
	v_mov_b32_e32 v50, v66
	s_nop 1
	v_permlane32_swap_b32_e32 v66, v50
	v_max_f32_e32 v50, v50, v50
	v_max_f32_e32 v51, v66, v66
	v_max_f32_e32 v50, v51, v50
	v_add_f32_e32 v51, 0x7149f2ca, v50
	v_cmp_ge_f32_e32 vcc, s16, v51
	v_max_f32_e32 v50, 0xf149f2ca, v50
	s_cmp_eq_u64 vcc, exec
	v_sub_f32_e32 v52, 0xf149f2ca, v50
	s_cselect_b64 vcc, -1, 0
	v_mul_f32_e32 v52, 0x3e0293ee, v52
	v_cndmask_b32_e32 v174, v50, v221, vcc
	s_lshl_b64 s[36:37], s[6:7], 1
	s_lshl_b32 s6, s33, 6
	v_exp_f32_e32 v52, v52
	v_mul_f32_e32 v50, 0xbe0293ee, v174
	s_and_b32 s33, s6, 0x300
	v_pk_fma_f32 v[148:149], v[48:49], s[12:13], v[50:51] op_sel_hi:[1,0,0]
	v_pk_fma_f32 v[154:155], v[46:47], s[12:13], v[50:51] op_sel_hi:[1,0,0]
	v_pk_fma_f32 v[160:161], v[44:45], s[12:13], v[50:51] op_sel_hi:[1,0,0]
	v_pk_fma_f32 v[146:147], v[42:43], s[12:13], v[50:51] op_sel_hi:[1,0,0]
	v_pk_fma_f32 v[150:151], v[40:41], s[12:13], v[50:51] op_sel_hi:[1,0,0]
	v_pk_fma_f32 v[152:153], v[38:39], s[12:13], v[50:51] op_sel_hi:[1,0,0]
	v_pk_fma_f32 v[156:157], v[36:37], s[12:13], v[50:51] op_sel_hi:[1,0,0]
	v_pk_fma_f32 v[158:159], v[34:35], s[12:13], v[50:51] op_sel_hi:[1,0,0]
	v_fmamk_f32 v18, v18, 0x3e0293ee, v50
	v_fmamk_f32 v19, v19, 0x3e0293ee, v50
	v_fmamk_f32 v20, v20, 0x3e0293ee, v50
	v_fmamk_f32 v21, v21, 0x3e0293ee, v50
	v_fmamk_f32 v22, v22, 0x3e0293ee, v50
	v_fmamk_f32 v23, v23, 0x3e0293ee, v50
	v_fmamk_f32 v24, v24, 0x3e0293ee, v50
	v_fmamk_f32 v25, v25, 0x3e0293ee, v50
	v_fmamk_f32 v26, v26, 0x3e0293ee, v50
	v_fmamk_f32 v27, v27, 0x3e0293ee, v50
	v_fmamk_f32 v28, v28, 0x3e0293ee, v50
	v_fmamk_f32 v29, v29, 0x3e0293ee, v50
	v_fmamk_f32 v30, v30, 0x3e0293ee, v50
	v_fmamk_f32 v31, v31, 0x3e0293ee, v50
	v_fmamk_f32 v32, v32, 0x3e0293ee, v50
	v_fmac_f32_e32 v50, 0x3e0293ee, v33
	s_add_u32 s6, s74, s33
	v_exp_f32_e32 v177, v18
	v_exp_f32_e32 v191, v19
	v_exp_f32_e32 v163, v20
	v_exp_f32_e32 v190, v21
	v_exp_f32_e32 v164, v22
	v_exp_f32_e32 v176, v23
	v_exp_f32_e32 v165, v24
	v_exp_f32_e32 v175, v25
	v_exp_f32_e32 v166, v26
	v_exp_f32_e32 v173, v27
	v_exp_f32_e32 v167, v28
	v_exp_f32_e32 v172, v29
	v_exp_f32_e32 v168, v30
	v_exp_f32_e32 v170, v31
	v_exp_f32_e32 v169, v32
	v_exp_f32_e32 v171, v50
	s_addc_u32 s7, s75, 0
	v_lshl_add_u64 v[186:187], v[182:183], 0, s[6:7]
	s_add_u32 s6, s72, s33
	v_cndmask_b32_e64 v224, v52, 1.0, vcc
	s_addc_u32 s7, s73, 0
	v_mov_b64_e32 v[64:65], v[16:17]
	v_mov_b64_e32 v[48:49], v[16:17]
	v_mov_b64_e32 v[32:33], v[16:17]
	v_lshl_add_u64 v[188:189], v[182:183], 0, s[6:7]
	v_mov_b64_e32 v[62:63], v[14:15]
	v_mov_b64_e32 v[60:61], v[12:13]
	v_mov_b64_e32 v[58:59], v[10:11]
	v_mov_b64_e32 v[56:57], v[8:9]
	v_mov_b64_e32 v[54:55], v[6:7]
	v_mov_b64_e32 v[52:53], v[4:5]
	v_mov_b64_e32 v[50:51], v[2:3]
	v_mov_b64_e32 v[46:47], v[14:15]
	v_mov_b64_e32 v[44:45], v[12:13]
	v_mov_b64_e32 v[42:43], v[10:11]
	v_mov_b64_e32 v[40:41], v[8:9]
	v_mov_b64_e32 v[38:39], v[6:7]
	v_mov_b64_e32 v[36:37], v[4:5]
	v_mov_b64_e32 v[34:35], v[2:3]
	v_mov_b64_e32 v[30:31], v[14:15]
	v_mov_b64_e32 v[28:29], v[12:13]
	v_mov_b64_e32 v[26:27], v[10:11]
	v_mov_b64_e32 v[24:25], v[8:9]
	v_mov_b64_e32 v[22:23], v[6:7]
	v_mov_b64_e32 v[20:21], v[4:5]
	v_mov_b64_e32 v[18:19], v[2:3]
